# bf16 norm phases P7/P10/P14: next 4-row pass prefetched into a second register set during the current pass (on v46)
# baseline (speedup 1.0000x reference)
; __device__ __forceinline__ void norm_mod_bf16_phase(const Ctx& F, const bf16_t* xin, const float* gain, const float* shift, const float* scale) {
;     ...
;     for (int ch = gw; ch < T / 32; ch += NGW) {
;         const int row0 = ch * 32, b = row0 / S;
;         float ga[2][8], sh[2][8];
; #pragma unroll
;         for (int j = 0; j < 2; ++j)
; #pragma unroll
;             for (int h = 0; h < 2; ++h) { const int c = 8 * ln + 512 * j + 4 * h; const f32x4 g = *(const f32x4*)(gain + c), sc = *(const f32x4*)(scale + (size_t)b * 6144 + c), s4 = *(const f32x4*)(shift + (size_t)b * 6144 + c);
; #pragma unroll
;                 for (int e = 0; e < 4; ++e) { ga[j][4 * h + e] = g[e] * (sc[e] + 1.0f); sh[j][4 * h + e] = s4[e]; } }
;         for (int r = 0; r < 32; r += 4) {
;             u32x4 raw[4][2]; float s[4];
; #pragma unroll
;             for (int u = 0; u < 4; ++u)
; #pragma unroll
;                 for (int j = 0; j < 2; ++j) raw[u][j] = *(const u32x4*)(xin + (size_t)(row0 + r + u) * D + 8 * ln + 512 * j);
.LBB0_983:
	s_ashr_i32 s19, s18, 31
	s_lshl_b64 s[4:5], s[18:19], 11
	s_add_u32 s26, s46, s4
	s_addc_u32 s27, s47, s5
	s_add_u32 s28, s33, s4
	s_addc_u32 s29, s42, s5
	s_ashr_i32 s21, s20, 31
	s_lshl_b64 s[4:5], s[20:21], 11
	s_add_u32 s30, s46, s4
	s_addc_u32 s31, s47, s5
	s_ashr_i32 s23, s22, 31
	s_lshl_b64 s[6:7], s[22:23], 11
	s_add_u32 s34, s44, s6
	s_addc_u32 s35, s45, s7
	s_add_u32 s36, s33, s4
	s_addc_u32 s37, s42, s5
	s_ashr_i32 s25, s24, 31
	s_lshl_b64 s[4:5], s[24:25], 11
	s_add_u32 s38, s46, s4
	s_addc_u32 s39, s47, s5
	s_add_u32 s40, s46, s6
	s_addc_u32 s41, s47, s7
	s_add_u32 s56, s33, s4
	s_addc_u32 s57, s42, s5
	s_ashr_i32 s4, s0, 31
	s_lshr_b32 s4, s4, 26
	s_add_i32 s4, s0, s4
	s_ashr_i32 s6, s4, 6
	v_mad_i64_i32 v[0:1], s[4:5], s6, v112, v[18:19]
	global_load_dwordx4 v[24:27], v[0:1], off
	global_load_dwordx4 v[28:31], v[0:1], off offset:16
	global_load_dwordx4 v[32:35], v[0:1], off offset:2048
	global_load_dwordx4 v[36:39], v[0:1], off offset:2064
	flat_load_dwordx4 v[40:43], v[16:17]
	flat_load_dwordx4 v[44:47], v[16:17] offset:16
	v_mad_i64_i32 v[56:57], s[4:5], s6, v112, v[20:21]
	flat_load_dwordx4 v[48:51], v[16:17] offset:2048
	flat_load_dwordx4 v[52:55], v[16:17] offset:2064
	global_load_dwordx4 v[0:3], v[56:57], off
	global_load_dwordx4 v[4:7], v[56:57], off offset:16
	global_load_dwordx4 v[8:11], v[56:57], off offset:2048
	global_load_dwordx4 v[12:15], v[56:57], off offset:2064
	s_mov_b32 s19, -4
	s_waitcnt vmcnt(0)
	v_pk_add_f32 v[24:25], v[24:25], 1.0 op_sel_hi:[1,0]
	v_pk_add_f32 v[26:27], v[26:27], 1.0 op_sel_hi:[1,0]
	v_pk_add_f32 v[28:29], v[28:29], 1.0 op_sel_hi:[1,0]
	v_pk_add_f32 v[30:31], v[30:31], 1.0 op_sel_hi:[1,0]
	v_pk_add_f32 v[32:33], v[32:33], 1.0 op_sel_hi:[1,0]
	v_pk_add_f32 v[34:35], v[34:35], 1.0 op_sel_hi:[1,0]
	v_pk_add_f32 v[36:37], v[36:37], 1.0 op_sel_hi:[1,0]
	v_pk_add_f32 v[38:39], v[38:39], 1.0 op_sel_hi:[1,0]
	s_waitcnt lgkmcnt(0)
	v_pk_mul_f32 v[24:25], v[40:41], v[24:25]
	v_pk_mul_f32 v[26:27], v[42:43], v[26:27]
	v_pk_mul_f32 v[28:29], v[44:45], v[28:29]
	v_pk_mul_f32 v[30:31], v[46:47], v[30:31]
	v_pk_mul_f32 v[32:33], v[48:49], v[32:33]
	v_pk_mul_f32 v[34:35], v[50:51], v[34:35]
	v_pk_mul_f32 v[36:37], v[52:53], v[36:37]
	v_pk_mul_f32 v[38:39], v[54:55], v[38:39]
	v_mov_b64_e32 v[224:225], v[22:23]
	v_lshl_add_u64 v[216:217], s[28:29], 0, v[224:225]
	v_lshl_add_u64 v[218:219], s[36:37], 0, v[224:225]
	v_lshl_add_u64 v[220:221], s[56:57], 0, v[224:225]
	v_lshl_add_u64 v[222:223], s[34:35], 0, v[224:225]
	global_load_dwordx4 v[184:187], v[216:217], off
	global_load_dwordx4 v[188:191], v[218:219], off
	global_load_dwordx4 v[192:195], v[220:221], off
	global_load_dwordx4 v[196:199], v[222:223], off offset:1024
	global_load_dwordx4 v[200:203], v[216:217], off offset:-1024
	global_load_dwordx4 v[204:207], v[218:219], off offset:-1024
	global_load_dwordx4 v[208:211], v[220:221], off offset:-1024
	global_load_dwordx4 v[212:215], v[222:223], off
	v_add_co_u32_e32 v224, vcc, 0x2000, v22
	s_nop 1
	v_addc_co_u32_e32 v225, vcc, 0, v23, vcc
	s_waitcnt vmcnt(0)
.LBB0_984:
	v_mov_b64_e32 v[60:61], v[184:185]
	v_mov_b64_e32 v[62:63], v[186:187]
	v_mov_b64_e32 v[68:69], v[188:189]
	v_mov_b64_e32 v[70:71], v[190:191]
	v_mov_b64_e32 v[72:73], v[192:193]
	v_mov_b64_e32 v[74:75], v[194:195]
	v_mov_b64_e32 v[116:117], v[196:197]
	v_mov_b64_e32 v[118:119], v[198:199]
	v_mov_b64_e32 v[84:85], v[200:201]
	v_mov_b64_e32 v[86:87], v[202:203]
	v_mov_b64_e32 v[88:89], v[204:205]
	v_mov_b64_e32 v[90:91], v[206:207]
	v_mov_b64_e32 v[120:121], v[208:209]
	v_mov_b64_e32 v[122:123], v[210:211]
	v_mov_b64_e32 v[124:125], v[212:213]
	v_mov_b64_e32 v[126:127], v[214:215]
	s_cmp_eq_u32 s19, 24
	s_cbranch_scc1 .Lnp_skip0
	v_lshl_add_u64 v[216:217], s[28:29], 0, v[224:225]
	v_lshl_add_u64 v[218:219], s[36:37], 0, v[224:225]
	v_lshl_add_u64 v[220:221], s[56:57], 0, v[224:225]
	v_lshl_add_u64 v[222:223], s[34:35], 0, v[224:225]
	global_load_dwordx4 v[184:187], v[216:217], off
	global_load_dwordx4 v[188:191], v[218:219], off
	global_load_dwordx4 v[192:195], v[220:221], off
	global_load_dwordx4 v[196:199], v[222:223], off offset:1024
	global_load_dwordx4 v[200:203], v[216:217], off offset:-1024
	global_load_dwordx4 v[204:207], v[218:219], off offset:-1024
	global_load_dwordx4 v[208:211], v[220:221], off offset:-1024
	global_load_dwordx4 v[212:215], v[222:223], off
; __device__ __forceinline__ float wave_sum_fast(float x) { x = reduce16(x); return (rl_(x, 0) + rl_(x, 16)) + (rl_(x, 32) + rl_(x, 48)); }
; __device__ __forceinline__ void norm_mod_bf16_phase(const Ctx& F, const bf16_t* xin, const float* gain, const float* shift, const float* scale) {
;     ...
;         for (int r = 0; r < 32; r += 4) {
;             u32x4 raw[4][2]; float s[4];
; #pragma unroll
;             for (int u = 0; u < 4; ++u)
; #pragma unroll
;                 for (int j = 0; j < 2; ++j) raw[u][j] = *(const u32x4*)(xin + (size_t)(row0 + r + u) * D + 8 * ln + 512 * j);
; #pragma unroll
;             for (int u = 0; u < 4; ++u) { s[u] = 0.f;
; #pragma unroll
;                 for (int j = 0; j < 2; ++j) { float f[8]; unpack8(raw[u][j], f);
; #pragma unroll
;                     for (int e = 0; e < 8; ++e) s[u] += f[e] * f[e]; }
;                 s[u] = wave_sum_fast(s[u]); }
.Lnp_skip0:
	v_lshl_add_u64 v[40:41], s[28:29], 0, v[22:23]
	v_lshl_add_u64 v[42:43], s[36:37], 0, v[22:23]
	v_lshl_add_u64 v[44:45], s[56:57], 0, v[22:23]
	v_lshl_add_u64 v[46:47], s[34:35], 0, v[22:23]
	v_lshl_add_u64 v[48:49], s[26:27], 0, v[22:23]
	v_add_co_u32_e32 v46, vcc, s48, v48
	v_lshl_add_u64 v[50:51], s[30:31], 0, v[22:23]
	s_nop 0
	v_addc_co_u32_e32 v47, vcc, 0, v49, vcc
	v_add_co_u32_e32 v44, vcc, s48, v50
	v_lshl_add_u64 v[52:53], s[38:39], 0, v[22:23]
	s_nop 0
	v_addc_co_u32_e32 v45, vcc, 0, v51, vcc
	v_add_co_u32_e32 v42, vcc, s48, v52
	v_lshl_add_u64 v[54:55], s[40:41], 0, v[22:23]
	s_nop 0
	v_addc_co_u32_e32 v43, vcc, 0, v53, vcc
	v_add_co_u32_e32 v40, vcc, s48, v54
	s_add_u32 s26, s26, 0x2000
	s_nop 0
	v_addc_co_u32_e32 v41, vcc, 0, v55, vcc
	s_addc_u32 s27, s27, 0
	s_add_i32 s19, s19, 4
	s_add_u32 s28, s28, 0x2000
	s_addc_u32 s29, s29, 0
	s_add_u32 s30, s30, 0x2000
	s_addc_u32 s31, s31, 0
	s_add_u32 s34, s34, 0x2000
	s_addc_u32 s35, s35, 0
	s_add_u32 s36, s36, 0x2000
	s_addc_u32 s37, s37, 0
	s_add_u32 s38, s38, 0x2000
	s_addc_u32 s39, s39, 0
	s_add_u32 s40, s40, 0x2000
	s_addc_u32 s41, s41, 0
	s_add_u32 s56, s56, 0x2000
	s_addc_u32 s57, s57, 0
	s_cmp_gt_u32 s19, 27
	v_and_b32_e32 v80, 0xffff0000, v62
	v_and_b32_e32 v64, 0xffff0000, v69
	v_and_b32_e32 v56, 0xffff0000, v74
	v_lshlrev_b32_e32 v57, 16, v74
	v_lshlrev_b32_e32 v110, 16, v84
	v_and_b32_e32 v111, 0xffff0000, v84
	v_lshlrev_b32_e32 v106, 16, v85
	v_and_b32_e32 v107, 0xffff0000, v85
	v_lshlrev_b32_e32 v92, 16, v91
	v_and_b32_e32 v93, 0xffff0000, v91
	v_lshlrev_b32_e32 v94, 16, v90
	v_and_b32_e32 v95, 0xffff0000, v90
	v_lshlrev_b32_e32 v100, 16, v88
	v_and_b32_e32 v101, 0xffff0000, v88
	v_lshlrev_b32_e32 v90, 16, v120
	v_and_b32_e32 v91, 0xffff0000, v120
	v_pk_mul_f32 v[146:147], v[110:111], v[110:111]
	v_and_b32_e32 v58, 0xffff0000, v75
	v_lshlrev_b32_e32 v59, 16, v75
	v_lshlrev_b32_e32 v102, 16, v87
	v_and_b32_e32 v103, 0xffff0000, v87
	v_lshlrev_b32_e32 v104, 16, v86
	v_and_b32_e32 v105, 0xffff0000, v86
	v_lshlrev_b32_e32 v96, 16, v89
	v_and_b32_e32 v97, 0xffff0000, v89
	v_lshlrev_b32_e32 v86, 16, v121
	v_and_b32_e32 v87, 0xffff0000, v121
	v_lshlrev_b32_e32 v74, 16, v124
	v_and_b32_e32 v75, 0xffff0000, v124
	v_pk_mul_f32 v[144:145], v[106:107], v[106:107]
	v_pk_mul_f32 v[156:157], v[100:101], v[100:101]
	v_pk_mul_f32 v[166:167], v[90:91], v[90:91]
	v_add_f32_e32 v115, v146, v147
	v_lshlrev_b32_e32 v65, 16, v69
	v_lshlrev_b32_e32 v98, 16, v68
	v_and_b32_e32 v99, 0xffff0000, v68
	v_lshlrev_b32_e32 v68, 16, v125
	v_and_b32_e32 v69, 0xffff0000, v125
	v_pk_mul_f32 v[154:155], v[96:97], v[96:97]
	v_pk_mul_f32 v[164:165], v[86:87], v[86:87]
	v_pk_mul_f32 v[176:177], v[74:75], v[74:75]
	v_add_f32_e32 v146, v156, v157
	v_add_f32_e32 v147, v166, v167
	v_add_f32_e32 v115, v144, v115
	v_lshlrev_b32_e32 v84, 16, v122
	v_and_b32_e32 v85, 0xffff0000, v122
	v_pk_mul_f32 v[142:143], v[104:105], v[104:105]
	v_pk_mul_f32 v[174:175], v[68:69], v[68:69]
	v_add_f32_e32 v156, v176, v177
	v_add_f32_e32 v144, v154, v146
	v_add_f32_e32 v146, v164, v147
	v_add_f32_e32 v115, v145, v115
	v_lshlrev_b32_e32 v81, 16, v62
	v_and_b32_e32 v82, 0xffff0000, v63
	v_lshlrev_b32_e32 v83, 16, v63
	v_lshlrev_b32_e32 v62, 16, v126
	v_and_b32_e32 v63, 0xffff0000, v126
	v_pk_mul_f32 v[152:153], v[94:95], v[94:95]
	v_pk_mul_f32 v[162:163], v[84:85], v[84:85]
	v_add_f32_e32 v147, v174, v156
	v_add_f32_e32 v144, v155, v144
	v_add_f32_e32 v145, v165, v146
	v_add_f32_e32 v115, v142, v115
	v_lshlrev_b32_e32 v76, 16, v123
	v_and_b32_e32 v77, 0xffff0000, v123
	v_pk_mul_f32 v[140:141], v[102:103], v[102:103]
	v_pk_mul_f32 v[172:173], v[62:63], v[62:63]
	v_add_f32_e32 v146, v175, v147
	v_add_f32_e32 v142, v152, v144
	v_add_f32_e32 v144, v162, v145
	v_add_f32_e32 v115, v143, v115
	v_and_b32_e32 v78, 0xffff0000, v61
	v_lshlrev_b32_e32 v79, 16, v61
	v_lshlrev_b32_e32 v108, 16, v60
	v_and_b32_e32 v109, 0xffff0000, v60
	v_lshlrev_b32_e32 v60, 16, v127
	v_and_b32_e32 v61, 0xffff0000, v127
	v_pk_mul_f32 v[150:151], v[92:93], v[92:93]
	v_pk_mul_f32 v[160:161], v[76:77], v[76:77]
	v_add_f32_e32 v145, v172, v146
	v_add_f32_e32 v142, v153, v142
	v_add_f32_e32 v143, v163, v144
	v_add_f32_e32 v115, v140, v115
	v_lshlrev_b32_e32 v88, 16, v72
	v_and_b32_e32 v89, 0xffff0000, v72
	v_pk_mul_f32 v[148:149], v[108:109], v[108:109]
	v_pk_mul_f32 v[170:171], v[60:61], v[60:61]
	v_add_f32_e32 v144, v173, v145
	v_add_f32_e32 v140, v150, v142
	v_add_f32_e32 v142, v160, v143
	v_add_f32_e32 v115, v141, v115
	v_and_b32_e32 v54, 0xffff0000, v73
	v_lshlrev_b32_e32 v55, 16, v73
	v_lshlrev_b32_e32 v72, 16, v116
	v_and_b32_e32 v73, 0xffff0000, v116
	v_pk_mul_f32 v[158:159], v[98:99], v[98:99]
	v_pk_mul_f32 v[168:169], v[88:89], v[88:89]
	v_add_f32_e32 v143, v170, v144
	v_add_f32_e32 v140, v151, v140
	v_add_f32_e32 v141, v161, v142
	v_add_f32_e32 v115, v148, v115
	v_and_b32_e32 v48, 0xffff0000, v117
	v_lshlrev_b32_e32 v49, 16, v117
	v_pk_mul_f32 v[116:117], v[78:79], v[78:79]
	v_pk_mul_f32 v[178:179], v[72:73], v[72:73]
	v_add_f32_e32 v142, v171, v143
	v_add_f32_e32 v140, v158, v140
	v_add_f32_e32 v141, v168, v141
	v_add_f32_e32 v115, v149, v115
	v_pk_mul_f32 v[122:123], v[64:65], v[64:65]
	v_pk_mul_f32 v[128:129], v[54:55], v[54:55]
	v_add_f32_e32 v142, v178, v142
	v_add_f32_e32 v140, v159, v140
	v_add_f32_e32 v141, v169, v141
	v_add_f32_e32 v115, v117, v115
	v_and_b32_e32 v66, 0xffff0000, v70
	v_lshlrev_b32_e32 v67, 16, v70
	v_and_b32_e32 v50, 0xffff0000, v118
	v_lshlrev_b32_e32 v51, 16, v118
	v_and_b32_e32 v52, 0xffff0000, v119
	v_lshlrev_b32_e32 v53, 16, v119
	v_pk_mul_f32 v[118:119], v[80:81], v[80:81]
	v_pk_mul_f32 v[134:135], v[48:49], v[48:49]
; __device__ __forceinline__ float wave_sum_fast(float x) { x = reduce16(x); return (rl_(x, 0) + rl_(x, 16)) + (rl_(x, 32) + rl_(x, 48)); }
; __device__ __forceinline__ void norm_mod_bf16_phase(const Ctx& F, const bf16_t* xin, const float* gain, const float* shift, const float* scale) {
;     ...
;             for (int u = 0; u < 4; ++u) { s[u] = 0.f;
; #pragma unroll
;                 for (int j = 0; j < 2; ++j) { float f[8]; unpack8(raw[u][j], f);
; #pragma unroll
;                     for (int e = 0; e < 8; ++e) s[u] += f[e] * f[e]; }
;                 s[u] = wave_sum_fast(s[u]); }
; #pragma unroll
;             for (int u = 0; u < 4; ++u) { const float rstd = 1.0f / sqrtf(s[u] * (1.0f / D) + 1e-6f);
	v_add_f32_e32 v142, v179, v142
	v_add_f32_e32 v117, v123, v140
	v_add_f32_e32 v123, v129, v141
	v_add_f32_e32 v115, v116, v115
	v_pk_mul_f32 v[124:125], v[66:67], v[66:67]
	v_pk_mul_f32 v[130:131], v[56:57], v[56:57]
	v_add_f32_e32 v129, v135, v142
	v_add_f32_e32 v116, v122, v117
	v_add_f32_e32 v117, v128, v123
	v_add_f32_e32 v115, v119, v115
	v_and_b32_e32 v70, 0xffff0000, v71
	v_lshlrev_b32_e32 v71, 16, v71
	v_pk_mul_f32 v[120:121], v[82:83], v[82:83]
	v_pk_mul_f32 v[136:137], v[50:51], v[50:51]
	v_add_f32_e32 v122, v134, v129
	v_add_f32_e32 v116, v125, v116
	v_add_f32_e32 v117, v131, v117
	v_add_f32_e32 v115, v118, v115
	v_pk_mul_f32 v[126:127], v[70:71], v[70:71]
	v_pk_mul_f32 v[132:133], v[58:59], v[58:59]
	v_add_f32_e32 v119, v137, v122
	v_add_f32_e32 v116, v124, v116
	v_add_f32_e32 v117, v130, v117
	v_add_f32_e32 v115, v121, v115
	v_pk_mul_f32 v[138:139], v[52:53], v[52:53]
	v_add_f32_e32 v118, v136, v119
	v_add_f32_e32 v116, v127, v116
	v_add_f32_e32 v117, v133, v117
	v_add_f32_e32 v115, v120, v115
	v_add_f32_e32 v118, v139, v118
	v_add_f32_e32 v116, v126, v116
	v_add_f32_e32 v117, v132, v117
	v_add_f32_dpp v115, v115, v115 quad_perm:[1,0,3,2] row_mask:0xf bank_mask:0xf bound_ctrl:1
	v_add_f32_e32 v118, v138, v118
	v_add_f32_dpp v116, v116, v116 quad_perm:[1,0,3,2] row_mask:0xf bank_mask:0xf bound_ctrl:1
	v_add_f32_dpp v117, v117, v117 quad_perm:[1,0,3,2] row_mask:0xf bank_mask:0xf bound_ctrl:1
	v_add_f32_dpp v115, v115, v115 quad_perm:[2,3,0,1] row_mask:0xf bank_mask:0xf bound_ctrl:1
	v_add_f32_dpp v118, v118, v118 quad_perm:[1,0,3,2] row_mask:0xf bank_mask:0xf bound_ctrl:1
	v_add_f32_dpp v116, v116, v116 quad_perm:[2,3,0,1] row_mask:0xf bank_mask:0xf bound_ctrl:1
	v_add_f32_dpp v117, v117, v117 quad_perm:[2,3,0,1] row_mask:0xf bank_mask:0xf bound_ctrl:1
	v_add_f32_dpp v115, v115, v115 row_half_mirror row_mask:0xf bank_mask:0xf bound_ctrl:1
	v_add_f32_dpp v118, v118, v118 quad_perm:[2,3,0,1] row_mask:0xf bank_mask:0xf bound_ctrl:1
	v_add_f32_dpp v116, v116, v116 row_half_mirror row_mask:0xf bank_mask:0xf bound_ctrl:1
	v_add_f32_dpp v117, v117, v117 row_half_mirror row_mask:0xf bank_mask:0xf bound_ctrl:1
	v_add_f32_dpp v115, v115, v115 row_mirror row_mask:0xf bank_mask:0xf bound_ctrl:1
	v_add_f32_dpp v118, v118, v118 row_half_mirror row_mask:0xf bank_mask:0xf bound_ctrl:1
	v_add_f32_dpp v116, v116, v116 row_mirror row_mask:0xf bank_mask:0xf bound_ctrl:1
	v_add_f32_dpp v117, v117, v117 row_mirror row_mask:0xf bank_mask:0xf bound_ctrl:1
	v_readlane_b32 s12, v115, 16
	v_readlane_b32 s13, v115, 48
	v_add_f32_dpp v118, v118, v118 row_mirror row_mask:0xf bank_mask:0xf bound_ctrl:1
	v_readlane_b32 s4, v115, 0
	v_readlane_b32 s5, v115, 32
	v_readlane_b32 s6, v116, 0
	v_readlane_b32 s14, v116, 16
	v_readlane_b32 s7, v116, 32
	v_readlane_b32 s15, v116, 48
	v_readlane_b32 s8, v117, 0
	v_readlane_b32 s16, v117, 16
	v_readlane_b32 s9, v117, 32
	v_readlane_b32 s17, v117, 48
	v_mov_b32_e32 v116, s12
	v_mov_b32_e32 v117, s13
	v_readlane_b32 s10, v118, 0
	v_readlane_b32 s21, v118, 16
	v_readlane_b32 s11, v118, 32
	v_readlane_b32 s23, v118, 48
	v_mov_b32_e32 v118, s14
	v_mov_b32_e32 v119, s15
	v_mov_b32_e32 v120, s16
	v_mov_b32_e32 v121, s17
	v_pk_add_f32 v[116:117], s[4:5], v[116:117]
	v_pk_add_f32 v[118:119], s[6:7], v[118:119]
	v_pk_add_f32 v[120:121], s[8:9], v[120:121]
	v_add_f32_e32 v115, v116, v117
	v_mov_b32_e32 v122, s21
	v_mov_b32_e32 v123, s23
	v_add_f32_e32 v116, v118, v119
	v_add_f32_e32 v117, v120, v121
	v_fmamk_f32 v115, v115, 0x3a800000, v113
	v_pk_add_f32 v[122:123], s[10:11], v[122:123]
	v_fmamk_f32 v116, v116, 0x3a800000, v113
	v_fmamk_f32 v117, v117, 0x3a800000, v113
	v_mul_f32_e32 v119, 0x4f800000, v115
	v_cmp_gt_f32_e64 s[8:9], s43, v115
	v_add_f32_e32 v118, v122, v123
	v_mul_f32_e32 v120, 0x4f800000, v116
	v_cmp_gt_f32_e32 vcc, s43, v116
	v_mul_f32_e32 v121, 0x4f800000, v117
	v_cmp_gt_f32_e64 s[4:5], s43, v117
	v_cndmask_b32_e64 v115, v115, v119, s[8:9]
	v_fmamk_f32 v118, v118, 0x3a800000, v113
	v_cndmask_b32_e32 v116, v116, v120, vcc
	v_cndmask_b32_e64 v117, v117, v121, s[4:5]
	v_sqrt_f32_e32 v119, v115
	v_mul_f32_e32 v122, 0x4f800000, v118
	v_cmp_gt_f32_e64 s[6:7], s43, v118
	v_sqrt_f32_e32 v120, v116
	v_sqrt_f32_e32 v121, v117
	v_cndmask_b32_e64 v118, v118, v122, s[6:7]
	v_sqrt_f32_e32 v122, v118
	v_add_u32_e32 v123, -1, v119
	v_add_u32_e32 v124, 1, v119
	v_add_u32_e32 v125, -1, v120
	v_add_u32_e32 v127, -1, v121
	v_fma_f32 v131, -v123, v119, v115
	v_add_u32_e32 v126, 1, v120
	v_add_u32_e32 v128, 1, v121
	v_fma_f32 v132, -v124, v119, v115
	v_fma_f32 v133, -v125, v120, v116
	v_fma_f32 v135, -v127, v121, v117
	v_cmp_ge_f32_e64 s[10:11], 0, v131
	v_add_u32_e32 v129, -1, v122
	v_fma_f32 v134, -v126, v120, v116
	v_fma_f32 v136, -v128, v121, v117
	v_cndmask_b32_e64 v119, v119, v123, s[10:11]
	v_cmp_ge_f32_e64 s[10:11], 0, v133
	v_cmp_ge_f32_e64 s[12:13], 0, v135
	v_cmp_lt_f32_e64 s[16:17], 0, v132
	v_add_u32_e32 v130, 1, v122
	v_fma_f32 v137, -v129, v122, v118
	v_cndmask_b32_e64 v120, v120, v125, s[10:11]
	v_cmp_lt_f32_e64 s[10:11], 0, v134
	v_cndmask_b32_e64 v121, v121, v127, s[12:13]
	v_cmp_lt_f32_e64 s[12:13], 0, v136
	v_cndmask_b32_e64 v119, v119, v124, s[16:17]
	v_fma_f32 v138, -v130, v122, v118
	v_cmp_ge_f32_e64 s[14:15], 0, v137
	v_cndmask_b32_e64 v120, v120, v126, s[10:11]
	v_cndmask_b32_e64 v121, v121, v128, s[12:13]
	v_mul_f32_e32 v123, 0x37800000, v119
	v_cndmask_b32_e64 v122, v122, v129, s[14:15]
	v_cmp_lt_f32_e64 s[14:15], 0, v138
	v_mul_f32_e32 v124, 0x37800000, v120
	v_mul_f32_e32 v125, 0x37800000, v121
	v_cndmask_b32_e64 v119, v119, v123, s[8:9]
	v_cmp_class_f32_e64 s[8:9], v115, v114
; __device__ __forceinline__ unsigned pk2(float lo, float hi) { f32x2 v = {lo, hi}; bf16x2_t b = __builtin_convertvector(v, bf16x2_t); return __builtin_bit_cast(unsigned, b); }
; __device__ __forceinline__ void norm_mod_bf16_phase(const Ctx& F, const bf16_t* xin, const float* gain, const float* shift, const float* scale) {
;     ...
;             for (int u = 0; u < 4; ++u) { const float rstd = 1.0f / sqrtf(s[u] * (1.0f / D) + 1e-6f);
; #pragma unroll
;                 for (int j = 0; j < 2; ++j) { float f[8]; unpack8(raw[u][j], f); float o[8];
; #pragma unroll
;                     for (int e = 0; e < 8; ++e) o[e] = f[e] * rstd * ga[j][e] + sh[j][e];
;                     u32x4 w; w.x = pk2(o[0], o[1]); w.y = pk2(o[2], o[3]); w.z = pk2(o[4], o[5]); w.w = pk2(o[6], o[7]);
	v_cndmask_b32_e64 v122, v122, v130, s[14:15]
	v_cndmask_b32_e32 v120, v120, v124, vcc
	v_cmp_class_f32_e32 vcc, v116, v114
	v_cndmask_b32_e64 v121, v121, v125, s[4:5]
	v_cmp_class_f32_e64 s[4:5], v117, v114
	v_cndmask_b32_e64 v115, v119, v115, s[8:9]
	v_mul_f32_e32 v126, 0x37800000, v122
	v_cndmask_b32_e32 v119, v120, v116, vcc
	v_cndmask_b32_e64 v117, v121, v117, s[4:5]
	v_div_scale_f32 v116, s[4:5], v115, v115, 1.0
	v_cndmask_b32_e64 v122, v122, v126, s[6:7]
	v_cmp_class_f32_e64 s[6:7], v118, v114
	v_div_scale_f32 v120, s[4:5], v119, v119, 1.0
	v_rcp_f32_e32 v127, v116
	v_cndmask_b32_e64 v124, v122, v118, s[6:7]
	v_div_scale_f32 v122, s[6:7], v117, v117, 1.0
	v_rcp_f32_e32 v128, v120
	v_div_scale_f32 v125, s[8:9], v124, v124, 1.0
	v_rcp_f32_e32 v129, v122
	v_rcp_f32_e32 v130, v125
	v_fma_f32 v131, -v116, v127, 1.0
	v_div_scale_f32 v118, vcc, 1.0, v115, 1.0
	v_fma_f32 v132, -v120, v128, 1.0
	v_fmac_f32_e32 v127, v131, v127
	v_div_scale_f32 v121, s[4:5], 1.0, v119, 1.0
	v_fma_f32 v133, -v122, v129, 1.0
	v_fmac_f32_e32 v128, v132, v128
	v_mul_f32_e32 v131, v118, v127
	v_div_scale_f32 v123, s[6:7], 1.0, v117, 1.0
	v_fma_f32 v134, -v125, v130, 1.0
	v_fmac_f32_e32 v129, v133, v129
	v_mul_f32_e32 v132, v121, v128
	v_fma_f32 v135, -v116, v131, v118
	v_div_scale_f32 v126, s[8:9], 1.0, v124, 1.0
	v_fmac_f32_e32 v130, v134, v130
	v_mul_f32_e32 v133, v123, v129
	v_fma_f32 v136, -v120, v132, v121
	v_fmac_f32_e32 v131, v135, v127
	v_mul_f32_e32 v134, v126, v130
	v_fma_f32 v137, -v122, v133, v123
	v_fmac_f32_e32 v132, v136, v128
	v_fma_f32 v116, -v116, v131, v118
	v_fma_f32 v138, -v125, v134, v126
	v_fmac_f32_e32 v133, v137, v129
	v_fma_f32 v118, -v120, v132, v121
	v_div_fmas_f32 v116, v116, v127, v131
	s_mov_b64 vcc, s[4:5]
	v_fmac_f32_e32 v134, v138, v130
	v_fma_f32 v120, -v122, v133, v123
	v_div_fixup_f32 v116, v116, v115, 1.0
	v_div_fmas_f32 v115, v118, v128, v132
	s_mov_b64 vcc, s[6:7]
	v_fma_f32 v125, -v125, v134, v126
	v_pk_mul_f32 v[110:111], v[116:117], v[110:111] op_sel_hi:[0,1]
	v_pk_mul_f32 v[106:107], v[116:117], v[106:107] op_sel_hi:[0,1]
	v_pk_mul_f32 v[104:105], v[116:117], v[104:105] op_sel_hi:[0,1]
	v_pk_mul_f32 v[102:103], v[116:117], v[102:103] op_sel_hi:[0,1]
	v_pk_mul_f32 v[108:109], v[116:117], v[108:109] op_sel_hi:[0,1]
	v_pk_mul_f32 v[78:79], v[116:117], v[78:79] op_sel_hi:[0,1]
	v_pk_mul_f32 v[80:81], v[116:117], v[80:81] op_sel_hi:[0,1]
	v_pk_mul_f32 v[82:83], v[116:117], v[82:83] op_sel_hi:[0,1]
	v_div_fixup_f32 v116, v115, v119, 1.0
	v_div_fmas_f32 v115, v120, v129, v133
	s_mov_b64 vcc, s[8:9]
	v_pk_fma_f32 v[110:111], v[24:25], v[110:111], v[0:1]
	v_pk_fma_f32 v[106:107], v[26:27], v[106:107], v[2:3]
	v_pk_fma_f32 v[104:105], v[28:29], v[104:105], v[4:5]
	v_pk_fma_f32 v[102:103], v[30:31], v[102:103], v[6:7]
	v_pk_fma_f32 v[108:109], v[32:33], v[108:109], v[8:9]
	v_pk_fma_f32 v[118:119], v[34:35], v[78:79], v[10:11] op_sel:[0,1,0] op_sel_hi:[1,0,1]
	v_pk_fma_f32 v[80:81], v[36:37], v[80:81], v[12:13] op_sel:[0,1,0] op_sel_hi:[1,0,1]
	v_pk_fma_f32 v[82:83], v[38:39], v[82:83], v[14:15] op_sel:[0,1,0] op_sel_hi:[1,0,1]
	v_pk_mul_f32 v[100:101], v[116:117], v[100:101] op_sel_hi:[0,1]
	v_pk_mul_f32 v[96:97], v[116:117], v[96:97] op_sel_hi:[0,1]
	v_pk_mul_f32 v[94:95], v[116:117], v[94:95] op_sel_hi:[0,1]
	v_pk_mul_f32 v[92:93], v[116:117], v[92:93] op_sel_hi:[0,1]
	v_pk_mul_f32 v[98:99], v[116:117], v[98:99] op_sel_hi:[0,1]
	v_pk_mul_f32 v[120:121], v[116:117], v[64:65] op_sel_hi:[0,1]
	v_pk_mul_f32 v[122:123], v[116:117], v[66:67] op_sel_hi:[0,1]
	v_pk_mul_f32 v[70:71], v[116:117], v[70:71] op_sel_hi:[0,1]
	v_div_fixup_f32 v116, v115, v117, 1.0
	v_div_fmas_f32 v115, v125, v130, v134
	v_cvt_pk_bf16_f32 v64, v110, v111
	v_cvt_pk_bf16_f32 v65, v106, v107
	v_cvt_pk_bf16_f32 v66, v104, v105
	v_cvt_pk_bf16_f32 v67, v102, v103
	v_cvt_pk_bf16_f32 v78, v108, v109
	v_cvt_pk_bf16_f32 v79, v118, v119
	v_cvt_pk_bf16_f32 v80, v80, v81
	v_cvt_pk_bf16_f32 v81, v82, v83
	v_pk_fma_f32 v[82:83], v[24:25], v[100:101], v[0:1]
; __device__ __forceinline__ unsigned pk2(float lo, float hi) { f32x2 v = {lo, hi}; bf16x2_t b = __builtin_convertvector(v, bf16x2_t); return __builtin_bit_cast(unsigned, b); }
; __device__ __forceinline__ void norm_mod_bf16_phase(const Ctx& F, const bf16_t* xin, const float* gain, const float* shift, const float* scale) {
;     ...
;                 for (int j = 0; j < 2; ++j) { float f[8]; unpack8(raw[u][j], f); float o[8];
; #pragma unroll
;                     for (int e = 0; e < 8; ++e) o[e] = f[e] * rstd * ga[j][e] + sh[j][e];
;                     u32x4 w; w.x = pk2(o[0], o[1]); w.y = pk2(o[2], o[3]); w.z = pk2(o[4], o[5]); w.w = pk2(o[6], o[7]);
;                     *(u32x4*)(hb + (size_t)(row0 + r + u) * D + 8 * ln + 512 * j) = w; } }
;         }
;     }
	v_pk_fma_f32 v[96:97], v[26:27], v[96:97], v[2:3]
	v_pk_fma_f32 v[94:95], v[28:29], v[94:95], v[4:5]
	v_pk_fma_f32 v[92:93], v[30:31], v[92:93], v[6:7]
	v_pk_fma_f32 v[70:71], v[38:39], v[70:71], v[14:15] op_sel:[0,1,0] op_sel_hi:[1,0,1]
	v_pk_mul_f32 v[90:91], v[116:117], v[90:91] op_sel_hi:[0,1]
	v_pk_mul_f32 v[86:87], v[116:117], v[86:87] op_sel_hi:[0,1]
	v_pk_mul_f32 v[84:85], v[116:117], v[84:85] op_sel_hi:[0,1]
	v_pk_mul_f32 v[76:77], v[116:117], v[76:77] op_sel_hi:[0,1]
	v_pk_mul_f32 v[58:59], v[116:117], v[58:59] op_sel_hi:[0,1]
	v_div_fixup_f32 v108, v115, v124, 1.0
	v_pk_fma_f32 v[98:99], v[32:33], v[98:99], v[8:9]
	v_pk_fma_f32 v[100:101], v[34:35], v[120:121], v[10:11] op_sel:[0,1,0] op_sel_hi:[1,0,1]
	v_pk_fma_f32 v[102:103], v[36:37], v[122:123], v[12:13] op_sel:[0,1,0] op_sel_hi:[1,0,1]
	v_pk_mul_f32 v[88:89], v[116:117], v[88:89] op_sel_hi:[0,1]
	v_pk_mul_f32 v[104:105], v[116:117], v[54:55] op_sel_hi:[0,1]
	v_pk_mul_f32 v[106:107], v[116:117], v[56:57] op_sel_hi:[0,1]
	global_store_dwordx4 v[46:47], v[64:67], off
	global_store_dwordx4 v[46:47], v[78:81], off offset:1024
	v_cvt_pk_bf16_f32 v54, v82, v83
	v_cvt_pk_bf16_f32 v55, v96, v97
	v_cvt_pk_bf16_f32 v56, v94, v95
	v_cvt_pk_bf16_f32 v57, v92, v93
	v_cvt_pk_bf16_f32 v67, v70, v71
	v_pk_fma_f32 v[46:47], v[24:25], v[90:91], v[0:1]
	v_pk_fma_f32 v[70:71], v[26:27], v[86:87], v[2:3]
	v_pk_fma_f32 v[78:79], v[28:29], v[84:85], v[4:5]
	v_pk_fma_f32 v[76:77], v[30:31], v[76:77], v[6:7]
	v_pk_fma_f32 v[58:59], v[38:39], v[58:59], v[14:15] op_sel:[0,1,0] op_sel_hi:[1,0,1]
	v_pk_mul_f32 v[74:75], v[108:109], v[74:75] op_sel_hi:[0,1]
	v_pk_mul_f32 v[68:69], v[108:109], v[68:69] op_sel_hi:[0,1]
	v_pk_mul_f32 v[62:63], v[108:109], v[62:63] op_sel_hi:[0,1]
	v_pk_mul_f32 v[60:61], v[108:109], v[60:61] op_sel_hi:[0,1]
	v_cvt_pk_bf16_f32 v64, v98, v99
	v_cvt_pk_bf16_f32 v65, v100, v101
	v_cvt_pk_bf16_f32 v66, v102, v103
	v_pk_fma_f32 v[80:81], v[32:33], v[88:89], v[8:9]
	v_pk_fma_f32 v[82:83], v[34:35], v[104:105], v[10:11] op_sel:[0,1,0] op_sel_hi:[1,0,1]
	v_pk_fma_f32 v[84:85], v[36:37], v[106:107], v[12:13] op_sel:[0,1,0] op_sel_hi:[1,0,1]
	v_pk_mul_f32 v[72:73], v[108:109], v[72:73] op_sel_hi:[0,1]
	v_pk_mul_f32 v[86:87], v[108:109], v[48:49] op_sel_hi:[0,1]
	v_pk_mul_f32 v[88:89], v[108:109], v[50:51] op_sel_hi:[0,1]
	v_pk_mul_f32 v[52:53], v[108:109], v[52:53] op_sel_hi:[0,1]
	global_store_dwordx4 v[44:45], v[54:57], off
	global_store_dwordx4 v[44:45], v[64:67], off offset:1024
	v_cvt_pk_bf16_f32 v44, v46, v47
	v_cvt_pk_bf16_f32 v45, v70, v71
	v_cvt_pk_bf16_f32 v46, v78, v79
	v_cvt_pk_bf16_f32 v47, v76, v77
	v_cvt_pk_bf16_f32 v51, v58, v59
	v_pk_fma_f32 v[54:55], v[24:25], v[74:75], v[0:1]
	v_pk_fma_f32 v[56:57], v[26:27], v[68:69], v[2:3]
	v_pk_fma_f32 v[58:59], v[28:29], v[62:63], v[4:5]
	v_pk_fma_f32 v[60:61], v[30:31], v[60:61], v[6:7]
	v_cvt_pk_bf16_f32 v48, v80, v81
	v_cvt_pk_bf16_f32 v49, v82, v83
	v_cvt_pk_bf16_f32 v50, v84, v85
	v_pk_fma_f32 v[62:63], v[32:33], v[72:73], v[8:9]
	v_pk_fma_f32 v[64:65], v[34:35], v[86:87], v[10:11] op_sel:[0,1,0] op_sel_hi:[1,0,1]
	v_pk_fma_f32 v[66:67], v[36:37], v[88:89], v[12:13] op_sel:[0,1,0] op_sel_hi:[1,0,1]
	v_pk_fma_f32 v[52:53], v[38:39], v[52:53], v[14:15] op_sel:[0,1,0] op_sel_hi:[1,0,1]
	global_store_dwordx4 v[42:43], v[44:47], off
	global_store_dwordx4 v[42:43], v[48:51], off offset:1024
	v_cvt_pk_bf16_f32 v42, v54, v55
	v_cvt_pk_bf16_f32 v43, v56, v57
	v_cvt_pk_bf16_f32 v44, v58, v59
	v_cvt_pk_bf16_f32 v45, v60, v61
	v_cvt_pk_bf16_f32 v46, v62, v63
	v_cvt_pk_bf16_f32 v47, v64, v65
	v_cvt_pk_bf16_f32 v48, v66, v67
	v_cvt_pk_bf16_f32 v49, v52, v53
	global_store_dwordx4 v[40:41], v[42:45], off
	global_store_dwordx4 v[40:41], v[46:49], off offset:1024
	s_waitcnt vmcnt(8)
	s_cbranch_scc0 .LBB0_984
	s_add_i32 s0, s0, s1
	s_add_i32 s18, s18, s3
	s_add_i32 s20, s20, s3
	s_add_i32 s22, s22, s3
	s_add_i32 s24, s24, s3
	s_cmpk_gt_i32 s0, 0x7ff
	s_cbranch_scc0 .LBB0_983

; __device__ __forceinline__ void norm_mod_bf16_phase(const Ctx& F, const bf16_t* xin, const float* gain, const float* shift, const float* scale) {
;     ...
;     for (int ch = gw; ch < T / 32; ch += NGW) {
;         const int row0 = ch * 32, b = row0 / S;
;         float ga[2][8], sh[2][8];
; #pragma unroll
;         for (int j = 0; j < 2; ++j)
; #pragma unroll
;             for (int h = 0; h < 2; ++h) { const int c = 8 * ln + 512 * j + 4 * h; const f32x4 g = *(const f32x4*)(gain + c), sc = *(const f32x4*)(scale + (size_t)b * 6144 + c), s4 = *(const f32x4*)(shift + (size_t)b * 6144 + c);
; #pragma unroll
;                 for (int e = 0; e < 4; ++e) { ga[j][4 * h + e] = g[e] * (sc[e] + 1.0f); sh[j][4 * h + e] = s4[e]; } }
;         for (int r = 0; r < 32; r += 4) {
;             u32x4 raw[4][2]; float s[4];
; #pragma unroll
;             for (int u = 0; u < 4; ++u)
; #pragma unroll
;                 for (int j = 0; j < 2; ++j) raw[u][j] = *(const u32x4*)(xin + (size_t)(row0 + r + u) * D + 8 * ln + 512 * j);
.LBB0_1203:
	s_ashr_i32 s19, s18, 31
	s_lshl_b64 s[4:5], s[18:19], 11
	s_add_u32 s26, s46, s4
	s_addc_u32 s27, s47, s5
	s_add_u32 s28, s33, s4
	s_addc_u32 s29, s42, s5
	s_ashr_i32 s21, s20, 31
	s_lshl_b64 s[4:5], s[20:21], 11
	s_add_u32 s30, s46, s4
	s_addc_u32 s31, s47, s5
	s_ashr_i32 s23, s22, 31
	s_lshl_b64 s[6:7], s[22:23], 11
	s_add_u32 s34, s44, s6
	s_addc_u32 s35, s45, s7
	s_add_u32 s36, s33, s4
	s_addc_u32 s37, s42, s5
	s_ashr_i32 s25, s24, 31
	s_lshl_b64 s[4:5], s[24:25], 11
	s_add_u32 s38, s46, s4
	s_addc_u32 s39, s47, s5
	s_add_u32 s40, s46, s6
	s_addc_u32 s41, s47, s7
	s_add_u32 s56, s33, s4
	s_addc_u32 s57, s42, s5
	s_ashr_i32 s4, s0, 31
	s_lshr_b32 s4, s4, 26
	s_add_i32 s4, s0, s4
	s_ashr_i32 s6, s4, 6
	v_mad_i64_i32 v[0:1], s[4:5], s6, v114, v[20:21]
	global_load_dwordx4 v[26:29], v[0:1], off
	global_load_dwordx4 v[30:33], v[0:1], off offset:16
	global_load_dwordx4 v[34:37], v[0:1], off offset:2048
	global_load_dwordx4 v[38:41], v[0:1], off offset:2064
	flat_load_dwordx4 v[42:45], v[16:17]
	flat_load_dwordx4 v[46:49], v[18:19]
	v_mad_i64_i32 v[58:59], s[4:5], s6, v114, v[22:23]
	flat_load_dwordx4 v[50:53], v[16:17] offset:2048
	flat_load_dwordx4 v[54:57], v[16:17] offset:2064
	global_load_dwordx4 v[0:3], v[58:59], off
	global_load_dwordx4 v[4:7], v[58:59], off offset:16
	global_load_dwordx4 v[8:11], v[58:59], off offset:2048
	global_load_dwordx4 v[12:15], v[58:59], off offset:2064
	s_mov_b32 s19, -4
	s_waitcnt vmcnt(0)
	v_pk_add_f32 v[26:27], v[26:27], 1.0 op_sel_hi:[1,0]
	v_pk_add_f32 v[28:29], v[28:29], 1.0 op_sel_hi:[1,0]
	v_pk_add_f32 v[30:31], v[30:31], 1.0 op_sel_hi:[1,0]
	v_pk_add_f32 v[32:33], v[32:33], 1.0 op_sel_hi:[1,0]
	v_pk_add_f32 v[34:35], v[34:35], 1.0 op_sel_hi:[1,0]
	v_pk_add_f32 v[36:37], v[36:37], 1.0 op_sel_hi:[1,0]
	v_pk_add_f32 v[38:39], v[38:39], 1.0 op_sel_hi:[1,0]
	v_pk_add_f32 v[40:41], v[40:41], 1.0 op_sel_hi:[1,0]
	s_waitcnt lgkmcnt(0)
	v_pk_mul_f32 v[26:27], v[42:43], v[26:27]
	v_pk_mul_f32 v[28:29], v[44:45], v[28:29]
	v_pk_mul_f32 v[30:31], v[46:47], v[30:31]
	v_pk_mul_f32 v[32:33], v[48:49], v[32:33]
	v_pk_mul_f32 v[34:35], v[50:51], v[34:35]
	v_pk_mul_f32 v[36:37], v[52:53], v[36:37]
	v_pk_mul_f32 v[38:39], v[54:55], v[38:39]
	v_pk_mul_f32 v[40:41], v[56:57], v[40:41]
	v_mov_b64_e32 v[224:225], v[24:25]
	v_lshl_add_u64 v[216:217], s[28:29], 0, v[224:225]
	v_lshl_add_u64 v[218:219], s[36:37], 0, v[224:225]
	v_lshl_add_u64 v[220:221], s[56:57], 0, v[224:225]
	v_lshl_add_u64 v[222:223], s[34:35], 0, v[224:225]
	global_load_dwordx4 v[184:187], v[216:217], off
	global_load_dwordx4 v[188:191], v[218:219], off
	global_load_dwordx4 v[192:195], v[220:221], off
	global_load_dwordx4 v[196:199], v[222:223], off offset:1024
	global_load_dwordx4 v[200:203], v[216:217], off offset:-1024
	global_load_dwordx4 v[204:207], v[218:219], off offset:-1024
	global_load_dwordx4 v[208:211], v[220:221], off offset:-1024
	global_load_dwordx4 v[212:215], v[222:223], off
	v_add_co_u32_e32 v224, vcc, 0x2000, v24
	s_nop 1
	v_addc_co_u32_e32 v225, vcc, 0, v25, vcc
	s_waitcnt vmcnt(0)
.LBB0_1204:
	v_mov_b64_e32 v[62:63], v[184:185]
	v_mov_b64_e32 v[64:65], v[186:187]
	v_mov_b64_e32 v[70:71], v[188:189]
	v_mov_b64_e32 v[72:73], v[190:191]
	v_mov_b64_e32 v[74:75], v[192:193]
	v_mov_b64_e32 v[76:77], v[194:195]
	v_mov_b64_e32 v[118:119], v[196:197]
	v_mov_b64_e32 v[120:121], v[198:199]
	v_mov_b64_e32 v[86:87], v[200:201]
	v_mov_b64_e32 v[88:89], v[202:203]
	v_mov_b64_e32 v[90:91], v[204:205]
	v_mov_b64_e32 v[92:93], v[206:207]
	v_mov_b64_e32 v[122:123], v[208:209]
	v_mov_b64_e32 v[124:125], v[210:211]
	v_mov_b64_e32 v[126:127], v[212:213]
	v_mov_b64_e32 v[128:129], v[214:215]
	s_cmp_eq_u32 s19, 24
	s_cbranch_scc1 .Lnp_skip1
	v_lshl_add_u64 v[216:217], s[28:29], 0, v[224:225]
	v_lshl_add_u64 v[218:219], s[36:37], 0, v[224:225]
	v_lshl_add_u64 v[220:221], s[56:57], 0, v[224:225]
	v_lshl_add_u64 v[222:223], s[34:35], 0, v[224:225]
	global_load_dwordx4 v[184:187], v[216:217], off
	global_load_dwordx4 v[188:191], v[218:219], off
	global_load_dwordx4 v[192:195], v[220:221], off
	global_load_dwordx4 v[196:199], v[222:223], off offset:1024
	global_load_dwordx4 v[200:203], v[216:217], off offset:-1024
	global_load_dwordx4 v[204:207], v[218:219], off offset:-1024
	global_load_dwordx4 v[208:211], v[220:221], off offset:-1024
	global_load_dwordx4 v[212:215], v[222:223], off
; __device__ __forceinline__ float wave_sum_fast(float x) { x = reduce16(x); return (rl_(x, 0) + rl_(x, 16)) + (rl_(x, 32) + rl_(x, 48)); }
; __device__ __forceinline__ void norm_mod_bf16_phase(const Ctx& F, const bf16_t* xin, const float* gain, const float* shift, const float* scale) {
;     ...
;         for (int r = 0; r < 32; r += 4) {
;             u32x4 raw[4][2]; float s[4];
; #pragma unroll
;             for (int u = 0; u < 4; ++u)
; #pragma unroll
;                 for (int j = 0; j < 2; ++j) raw[u][j] = *(const u32x4*)(xin + (size_t)(row0 + r + u) * D + 8 * ln + 512 * j);
; #pragma unroll
;             for (int u = 0; u < 4; ++u) { s[u] = 0.f;
; #pragma unroll
;                 for (int j = 0; j < 2; ++j) { float f[8]; unpack8(raw[u][j], f);
; #pragma unroll
;                     for (int e = 0; e < 8; ++e) s[u] += f[e] * f[e]; }
;                 s[u] = wave_sum_fast(s[u]); }
.Lnp_skip1:
	v_lshl_add_u64 v[42:43], s[28:29], 0, v[24:25]
	v_lshl_add_u64 v[44:45], s[36:37], 0, v[24:25]
	v_lshl_add_u64 v[46:47], s[56:57], 0, v[24:25]
	v_lshl_add_u64 v[48:49], s[34:35], 0, v[24:25]
	v_lshl_add_u64 v[50:51], s[26:27], 0, v[24:25]
	v_add_co_u32_e32 v48, vcc, s48, v50
	v_lshl_add_u64 v[52:53], s[30:31], 0, v[24:25]
	s_nop 0
	v_addc_co_u32_e32 v49, vcc, 0, v51, vcc
	v_add_co_u32_e32 v46, vcc, s48, v52
	v_lshl_add_u64 v[54:55], s[38:39], 0, v[24:25]
	s_nop 0
	v_addc_co_u32_e32 v47, vcc, 0, v53, vcc
	v_add_co_u32_e32 v44, vcc, s48, v54
	v_lshl_add_u64 v[56:57], s[40:41], 0, v[24:25]
	s_nop 0
	v_addc_co_u32_e32 v45, vcc, 0, v55, vcc
	v_add_co_u32_e32 v42, vcc, s48, v56
	s_add_u32 s26, s26, 0x2000
	s_nop 0
	v_addc_co_u32_e32 v43, vcc, 0, v57, vcc
	s_addc_u32 s27, s27, 0
	s_add_i32 s19, s19, 4
	s_add_u32 s28, s28, 0x2000
	s_addc_u32 s29, s29, 0
	s_add_u32 s30, s30, 0x2000
	s_addc_u32 s31, s31, 0
	s_add_u32 s34, s34, 0x2000
	s_addc_u32 s35, s35, 0
	s_add_u32 s36, s36, 0x2000
	s_addc_u32 s37, s37, 0
	s_add_u32 s38, s38, 0x2000
	s_addc_u32 s39, s39, 0
	s_add_u32 s40, s40, 0x2000
	s_addc_u32 s41, s41, 0
	s_add_u32 s56, s56, 0x2000
	s_addc_u32 s57, s57, 0
	s_cmp_gt_u32 s19, 27
	v_and_b32_e32 v82, 0xffff0000, v64
	v_and_b32_e32 v66, 0xffff0000, v71
	v_and_b32_e32 v58, 0xffff0000, v76
	v_lshlrev_b32_e32 v59, 16, v76
	v_lshlrev_b32_e32 v112, 16, v86
	v_and_b32_e32 v113, 0xffff0000, v86
	v_lshlrev_b32_e32 v108, 16, v87
	v_and_b32_e32 v109, 0xffff0000, v87
	v_lshlrev_b32_e32 v94, 16, v93
	v_and_b32_e32 v95, 0xffff0000, v93
	v_lshlrev_b32_e32 v96, 16, v92
	v_and_b32_e32 v97, 0xffff0000, v92
	v_lshlrev_b32_e32 v102, 16, v90
	v_and_b32_e32 v103, 0xffff0000, v90
	v_lshlrev_b32_e32 v92, 16, v122
	v_and_b32_e32 v93, 0xffff0000, v122
	v_pk_mul_f32 v[148:149], v[112:113], v[112:113]
	v_and_b32_e32 v60, 0xffff0000, v77
	v_lshlrev_b32_e32 v61, 16, v77
	v_lshlrev_b32_e32 v104, 16, v89
	v_and_b32_e32 v105, 0xffff0000, v89
	v_lshlrev_b32_e32 v106, 16, v88
	v_and_b32_e32 v107, 0xffff0000, v88
	v_lshlrev_b32_e32 v98, 16, v91
	v_and_b32_e32 v99, 0xffff0000, v91
	v_lshlrev_b32_e32 v88, 16, v123
	v_and_b32_e32 v89, 0xffff0000, v123
	v_lshlrev_b32_e32 v76, 16, v126
	v_and_b32_e32 v77, 0xffff0000, v126
	v_pk_mul_f32 v[146:147], v[108:109], v[108:109]
	v_pk_mul_f32 v[158:159], v[102:103], v[102:103]
	v_pk_mul_f32 v[168:169], v[92:93], v[92:93]
	v_add_f32_e32 v117, v148, v149
	v_lshlrev_b32_e32 v67, 16, v71
	v_lshlrev_b32_e32 v100, 16, v70
	v_and_b32_e32 v101, 0xffff0000, v70
	v_lshlrev_b32_e32 v70, 16, v127
	v_and_b32_e32 v71, 0xffff0000, v127
	v_pk_mul_f32 v[156:157], v[98:99], v[98:99]
	v_pk_mul_f32 v[166:167], v[88:89], v[88:89]
	v_pk_mul_f32 v[178:179], v[76:77], v[76:77]
	v_add_f32_e32 v148, v158, v159
	v_add_f32_e32 v149, v168, v169
	v_add_f32_e32 v117, v146, v117
	v_lshlrev_b32_e32 v86, 16, v124
	v_and_b32_e32 v87, 0xffff0000, v124
	v_pk_mul_f32 v[144:145], v[106:107], v[106:107]
	v_pk_mul_f32 v[176:177], v[70:71], v[70:71]
	v_add_f32_e32 v158, v178, v179
	v_add_f32_e32 v146, v156, v148
	v_add_f32_e32 v148, v166, v149
	v_add_f32_e32 v117, v147, v117
	v_lshlrev_b32_e32 v83, 16, v64
	v_and_b32_e32 v84, 0xffff0000, v65
	v_lshlrev_b32_e32 v85, 16, v65
	v_lshlrev_b32_e32 v64, 16, v128
	v_and_b32_e32 v65, 0xffff0000, v128
	v_pk_mul_f32 v[154:155], v[96:97], v[96:97]
	v_pk_mul_f32 v[164:165], v[86:87], v[86:87]
	v_add_f32_e32 v149, v176, v158
	v_add_f32_e32 v146, v157, v146
	v_add_f32_e32 v147, v167, v148
	v_add_f32_e32 v117, v144, v117
	v_lshlrev_b32_e32 v78, 16, v125
	v_and_b32_e32 v79, 0xffff0000, v125
	v_pk_mul_f32 v[142:143], v[104:105], v[104:105]
	v_pk_mul_f32 v[174:175], v[64:65], v[64:65]
	v_add_f32_e32 v148, v177, v149
	v_add_f32_e32 v144, v154, v146
	v_add_f32_e32 v146, v164, v147
	v_add_f32_e32 v117, v145, v117
	v_and_b32_e32 v80, 0xffff0000, v63
	v_lshlrev_b32_e32 v81, 16, v63
	v_lshlrev_b32_e32 v110, 16, v62
	v_and_b32_e32 v111, 0xffff0000, v62
	v_lshlrev_b32_e32 v62, 16, v129
	v_and_b32_e32 v63, 0xffff0000, v129
	v_pk_mul_f32 v[152:153], v[94:95], v[94:95]
	v_pk_mul_f32 v[162:163], v[78:79], v[78:79]
	v_add_f32_e32 v147, v174, v148
	v_add_f32_e32 v144, v155, v144
	v_add_f32_e32 v145, v165, v146
	v_add_f32_e32 v117, v142, v117
	v_lshlrev_b32_e32 v90, 16, v74
	v_and_b32_e32 v91, 0xffff0000, v74
	v_pk_mul_f32 v[150:151], v[110:111], v[110:111]
	v_pk_mul_f32 v[172:173], v[62:63], v[62:63]
	v_add_f32_e32 v146, v175, v147
	v_add_f32_e32 v142, v152, v144
	v_add_f32_e32 v144, v162, v145
	v_add_f32_e32 v117, v143, v117
	v_and_b32_e32 v56, 0xffff0000, v75
	v_lshlrev_b32_e32 v57, 16, v75
	v_lshlrev_b32_e32 v74, 16, v118
	v_and_b32_e32 v75, 0xffff0000, v118
	v_pk_mul_f32 v[160:161], v[100:101], v[100:101]
	v_pk_mul_f32 v[170:171], v[90:91], v[90:91]
	v_add_f32_e32 v145, v172, v146
	v_add_f32_e32 v142, v153, v142
	v_add_f32_e32 v143, v163, v144
	v_add_f32_e32 v117, v150, v117
	v_and_b32_e32 v50, 0xffff0000, v119
	v_lshlrev_b32_e32 v51, 16, v119
	v_pk_mul_f32 v[118:119], v[80:81], v[80:81]
	v_pk_mul_f32 v[180:181], v[74:75], v[74:75]
	v_add_f32_e32 v144, v173, v145
	v_add_f32_e32 v142, v160, v142
	v_add_f32_e32 v143, v170, v143
	v_add_f32_e32 v117, v151, v117
	v_pk_mul_f32 v[124:125], v[66:67], v[66:67]
	v_pk_mul_f32 v[130:131], v[56:57], v[56:57]
	v_add_f32_e32 v144, v180, v144
	v_add_f32_e32 v142, v161, v142
	v_add_f32_e32 v143, v171, v143
	v_add_f32_e32 v117, v119, v117
	v_and_b32_e32 v68, 0xffff0000, v72
	v_lshlrev_b32_e32 v69, 16, v72
	v_and_b32_e32 v52, 0xffff0000, v120
	v_lshlrev_b32_e32 v53, 16, v120
	v_and_b32_e32 v54, 0xffff0000, v121
	v_lshlrev_b32_e32 v55, 16, v121
	v_pk_mul_f32 v[120:121], v[82:83], v[82:83]
	v_pk_mul_f32 v[136:137], v[50:51], v[50:51]
; __device__ __forceinline__ float wave_sum_fast(float x) { x = reduce16(x); return (rl_(x, 0) + rl_(x, 16)) + (rl_(x, 32) + rl_(x, 48)); }
; __device__ __forceinline__ void norm_mod_bf16_phase(const Ctx& F, const bf16_t* xin, const float* gain, const float* shift, const float* scale) {
;     ...
;             for (int u = 0; u < 4; ++u) { s[u] = 0.f;
; #pragma unroll
;                 for (int j = 0; j < 2; ++j) { float f[8]; unpack8(raw[u][j], f);
; #pragma unroll
;                     for (int e = 0; e < 8; ++e) s[u] += f[e] * f[e]; }
;                 s[u] = wave_sum_fast(s[u]); }
; #pragma unroll
;             for (int u = 0; u < 4; ++u) { const float rstd = 1.0f / sqrtf(s[u] * (1.0f / D) + 1e-6f);
	v_add_f32_e32 v144, v181, v144
	v_add_f32_e32 v119, v125, v142
	v_add_f32_e32 v125, v131, v143
	v_add_f32_e32 v117, v118, v117
	v_pk_mul_f32 v[126:127], v[68:69], v[68:69]
	v_pk_mul_f32 v[132:133], v[58:59], v[58:59]
	v_add_f32_e32 v131, v137, v144
	v_add_f32_e32 v118, v124, v119
	v_add_f32_e32 v119, v130, v125
	v_add_f32_e32 v117, v121, v117
	v_and_b32_e32 v72, 0xffff0000, v73
	v_lshlrev_b32_e32 v73, 16, v73
	v_pk_mul_f32 v[122:123], v[84:85], v[84:85]
	v_pk_mul_f32 v[138:139], v[52:53], v[52:53]
	v_add_f32_e32 v124, v136, v131
	v_add_f32_e32 v118, v127, v118
	v_add_f32_e32 v119, v133, v119
	v_add_f32_e32 v117, v120, v117
	v_pk_mul_f32 v[128:129], v[72:73], v[72:73]
	v_pk_mul_f32 v[134:135], v[60:61], v[60:61]
	v_add_f32_e32 v121, v139, v124
	v_add_f32_e32 v118, v126, v118
	v_add_f32_e32 v119, v132, v119
	v_add_f32_e32 v117, v123, v117
	v_pk_mul_f32 v[140:141], v[54:55], v[54:55]
	v_add_f32_e32 v120, v138, v121
	v_add_f32_e32 v118, v129, v118
	v_add_f32_e32 v119, v135, v119
	v_add_f32_e32 v117, v122, v117
	v_add_f32_e32 v120, v141, v120
	v_add_f32_e32 v118, v128, v118
	v_add_f32_e32 v119, v134, v119
	v_add_f32_dpp v117, v117, v117 quad_perm:[1,0,3,2] row_mask:0xf bank_mask:0xf bound_ctrl:1
	v_add_f32_e32 v120, v140, v120
	v_add_f32_dpp v118, v118, v118 quad_perm:[1,0,3,2] row_mask:0xf bank_mask:0xf bound_ctrl:1
	v_add_f32_dpp v119, v119, v119 quad_perm:[1,0,3,2] row_mask:0xf bank_mask:0xf bound_ctrl:1
	v_add_f32_dpp v117, v117, v117 quad_perm:[2,3,0,1] row_mask:0xf bank_mask:0xf bound_ctrl:1
	v_add_f32_dpp v120, v120, v120 quad_perm:[1,0,3,2] row_mask:0xf bank_mask:0xf bound_ctrl:1
	v_add_f32_dpp v118, v118, v118 quad_perm:[2,3,0,1] row_mask:0xf bank_mask:0xf bound_ctrl:1
	v_add_f32_dpp v119, v119, v119 quad_perm:[2,3,0,1] row_mask:0xf bank_mask:0xf bound_ctrl:1
	v_add_f32_dpp v117, v117, v117 row_half_mirror row_mask:0xf bank_mask:0xf bound_ctrl:1
	v_add_f32_dpp v120, v120, v120 quad_perm:[2,3,0,1] row_mask:0xf bank_mask:0xf bound_ctrl:1
	v_add_f32_dpp v118, v118, v118 row_half_mirror row_mask:0xf bank_mask:0xf bound_ctrl:1
	v_add_f32_dpp v119, v119, v119 row_half_mirror row_mask:0xf bank_mask:0xf bound_ctrl:1
	v_add_f32_dpp v117, v117, v117 row_mirror row_mask:0xf bank_mask:0xf bound_ctrl:1
	v_add_f32_dpp v120, v120, v120 row_half_mirror row_mask:0xf bank_mask:0xf bound_ctrl:1
	v_add_f32_dpp v118, v118, v118 row_mirror row_mask:0xf bank_mask:0xf bound_ctrl:1
	v_add_f32_dpp v119, v119, v119 row_mirror row_mask:0xf bank_mask:0xf bound_ctrl:1
	v_readlane_b32 s12, v117, 16
	v_readlane_b32 s13, v117, 48
	v_add_f32_dpp v120, v120, v120 row_mirror row_mask:0xf bank_mask:0xf bound_ctrl:1
	v_readlane_b32 s4, v117, 0
	v_readlane_b32 s5, v117, 32
	v_readlane_b32 s6, v118, 0
	v_readlane_b32 s14, v118, 16
	v_readlane_b32 s7, v118, 32
	v_readlane_b32 s15, v118, 48
	v_readlane_b32 s8, v119, 0
	v_readlane_b32 s16, v119, 16
	v_readlane_b32 s9, v119, 32
	v_readlane_b32 s17, v119, 48
	v_mov_b32_e32 v118, s12
	v_mov_b32_e32 v119, s13
	v_readlane_b32 s10, v120, 0
	v_readlane_b32 s21, v120, 16
	v_readlane_b32 s11, v120, 32
	v_readlane_b32 s23, v120, 48
	v_mov_b32_e32 v120, s14
	v_mov_b32_e32 v121, s15
	v_mov_b32_e32 v122, s16
	v_mov_b32_e32 v123, s17
	v_pk_add_f32 v[118:119], s[4:5], v[118:119]
	v_pk_add_f32 v[120:121], s[6:7], v[120:121]
	v_pk_add_f32 v[122:123], s[8:9], v[122:123]
	v_add_f32_e32 v117, v118, v119
	v_mov_b32_e32 v124, s21
	v_mov_b32_e32 v125, s23
	v_add_f32_e32 v118, v120, v121
	v_add_f32_e32 v119, v122, v123
	v_fmamk_f32 v117, v117, 0x3a800000, v115
	v_pk_add_f32 v[124:125], s[10:11], v[124:125]
	v_fmamk_f32 v118, v118, 0x3a800000, v115
	v_fmamk_f32 v119, v119, 0x3a800000, v115
	v_mul_f32_e32 v121, 0x4f800000, v117
	v_cmp_gt_f32_e64 s[8:9], s43, v117
	v_add_f32_e32 v120, v124, v125
	v_mul_f32_e32 v122, 0x4f800000, v118
	v_cmp_gt_f32_e32 vcc, s43, v118
	v_mul_f32_e32 v123, 0x4f800000, v119
	v_cmp_gt_f32_e64 s[4:5], s43, v119
	v_cndmask_b32_e64 v117, v117, v121, s[8:9]
	v_fmamk_f32 v120, v120, 0x3a800000, v115
	v_cndmask_b32_e32 v118, v118, v122, vcc
	v_cndmask_b32_e64 v119, v119, v123, s[4:5]
	v_sqrt_f32_e32 v121, v117
	v_mul_f32_e32 v124, 0x4f800000, v120
	v_cmp_gt_f32_e64 s[6:7], s43, v120
	v_sqrt_f32_e32 v122, v118
	v_sqrt_f32_e32 v123, v119
	v_cndmask_b32_e64 v120, v120, v124, s[6:7]
	v_sqrt_f32_e32 v124, v120
	v_add_u32_e32 v125, -1, v121
	v_add_u32_e32 v126, 1, v121
	v_add_u32_e32 v127, -1, v122
	v_add_u32_e32 v129, -1, v123
	v_fma_f32 v133, -v125, v121, v117
	v_add_u32_e32 v128, 1, v122
	v_add_u32_e32 v130, 1, v123
	v_fma_f32 v134, -v126, v121, v117
	v_fma_f32 v135, -v127, v122, v118
	v_fma_f32 v137, -v129, v123, v119
	v_cmp_ge_f32_e64 s[10:11], 0, v133
	v_add_u32_e32 v131, -1, v124
	v_fma_f32 v136, -v128, v122, v118
	v_fma_f32 v138, -v130, v123, v119
	v_cndmask_b32_e64 v121, v121, v125, s[10:11]
	v_cmp_ge_f32_e64 s[10:11], 0, v135
	v_cmp_ge_f32_e64 s[12:13], 0, v137
	v_cmp_lt_f32_e64 s[16:17], 0, v134
	v_add_u32_e32 v132, 1, v124
	v_fma_f32 v139, -v131, v124, v120
	v_cndmask_b32_e64 v122, v122, v127, s[10:11]
	v_cmp_lt_f32_e64 s[10:11], 0, v136
	v_cndmask_b32_e64 v123, v123, v129, s[12:13]
	v_cmp_lt_f32_e64 s[12:13], 0, v138
	v_cndmask_b32_e64 v121, v121, v126, s[16:17]
	v_fma_f32 v140, -v132, v124, v120
	v_cmp_ge_f32_e64 s[14:15], 0, v139
	v_cndmask_b32_e64 v122, v122, v128, s[10:11]
	v_cndmask_b32_e64 v123, v123, v130, s[12:13]
	v_mul_f32_e32 v125, 0x37800000, v121
	v_cndmask_b32_e64 v124, v124, v131, s[14:15]
	v_cmp_lt_f32_e64 s[14:15], 0, v140
	v_mul_f32_e32 v126, 0x37800000, v122
	v_mul_f32_e32 v127, 0x37800000, v123
	v_cndmask_b32_e64 v121, v121, v125, s[8:9]
	v_cmp_class_f32_e64 s[8:9], v117, v116
; __device__ __forceinline__ unsigned pk2(float lo, float hi) { f32x2 v = {lo, hi}; bf16x2_t b = __builtin_convertvector(v, bf16x2_t); return __builtin_bit_cast(unsigned, b); }
; __device__ __forceinline__ void norm_mod_bf16_phase(const Ctx& F, const bf16_t* xin, const float* gain, const float* shift, const float* scale) {
;     ...
;             for (int u = 0; u < 4; ++u) { const float rstd = 1.0f / sqrtf(s[u] * (1.0f / D) + 1e-6f);
; #pragma unroll
;                 for (int j = 0; j < 2; ++j) { float f[8]; unpack8(raw[u][j], f); float o[8];
; #pragma unroll
;                     for (int e = 0; e < 8; ++e) o[e] = f[e] * rstd * ga[j][e] + sh[j][e];
;                     u32x4 w; w.x = pk2(o[0], o[1]); w.y = pk2(o[2], o[3]); w.z = pk2(o[4], o[5]); w.w = pk2(o[6], o[7]);
;                     *(u32x4*)(hb + (size_t)(row0 + r + u) * D + 8 * ln + 512 * j) = w; } }
	v_cndmask_b32_e64 v124, v124, v132, s[14:15]
	v_cndmask_b32_e32 v122, v122, v126, vcc
	v_cmp_class_f32_e32 vcc, v118, v116
	v_cndmask_b32_e64 v123, v123, v127, s[4:5]
	v_cmp_class_f32_e64 s[4:5], v119, v116
	v_cndmask_b32_e64 v117, v121, v117, s[8:9]
	v_mul_f32_e32 v128, 0x37800000, v124
	v_cndmask_b32_e32 v121, v122, v118, vcc
	v_cndmask_b32_e64 v119, v123, v119, s[4:5]
	v_div_scale_f32 v118, s[4:5], v117, v117, 1.0
	v_cndmask_b32_e64 v124, v124, v128, s[6:7]
	v_cmp_class_f32_e64 s[6:7], v120, v116
	v_div_scale_f32 v122, s[4:5], v121, v121, 1.0
	v_rcp_f32_e32 v129, v118
	v_cndmask_b32_e64 v126, v124, v120, s[6:7]
	v_div_scale_f32 v124, s[6:7], v119, v119, 1.0
	v_rcp_f32_e32 v130, v122
	v_div_scale_f32 v127, s[8:9], v126, v126, 1.0
	v_rcp_f32_e32 v131, v124
	v_rcp_f32_e32 v132, v127
	v_fma_f32 v133, -v118, v129, 1.0
	v_div_scale_f32 v120, vcc, 1.0, v117, 1.0
	v_fma_f32 v134, -v122, v130, 1.0
	v_fmac_f32_e32 v129, v133, v129
	v_div_scale_f32 v123, s[4:5], 1.0, v121, 1.0
	v_fma_f32 v135, -v124, v131, 1.0
	v_fmac_f32_e32 v130, v134, v130
	v_mul_f32_e32 v133, v120, v129
	v_div_scale_f32 v125, s[6:7], 1.0, v119, 1.0
	v_fma_f32 v136, -v127, v132, 1.0
	v_fmac_f32_e32 v131, v135, v131
	v_mul_f32_e32 v134, v123, v130
	v_fma_f32 v137, -v118, v133, v120
	v_div_scale_f32 v128, s[8:9], 1.0, v126, 1.0
	v_fmac_f32_e32 v132, v136, v132
	v_mul_f32_e32 v135, v125, v131
	v_fma_f32 v138, -v122, v134, v123
	v_fmac_f32_e32 v133, v137, v129
	v_mul_f32_e32 v136, v128, v132
	v_fma_f32 v139, -v124, v135, v125
	v_fmac_f32_e32 v134, v138, v130
	v_fma_f32 v118, -v118, v133, v120
	v_fma_f32 v140, -v127, v136, v128
	v_fmac_f32_e32 v135, v139, v131
	v_fma_f32 v120, -v122, v134, v123
	v_div_fmas_f32 v118, v118, v129, v133
	s_mov_b64 vcc, s[4:5]
	v_fmac_f32_e32 v136, v140, v132
	v_fma_f32 v122, -v124, v135, v125
	v_div_fixup_f32 v118, v118, v117, 1.0
	v_div_fmas_f32 v117, v120, v130, v134
	s_mov_b64 vcc, s[6:7]
	v_fma_f32 v127, -v127, v136, v128
	v_pk_mul_f32 v[112:113], v[118:119], v[112:113] op_sel_hi:[0,1]
	v_pk_mul_f32 v[108:109], v[118:119], v[108:109] op_sel_hi:[0,1]
	v_pk_mul_f32 v[106:107], v[118:119], v[106:107] op_sel_hi:[0,1]
	v_pk_mul_f32 v[104:105], v[118:119], v[104:105] op_sel_hi:[0,1]
	v_pk_mul_f32 v[110:111], v[118:119], v[110:111] op_sel_hi:[0,1]
	v_pk_mul_f32 v[80:81], v[118:119], v[80:81] op_sel_hi:[0,1]
	v_pk_mul_f32 v[82:83], v[118:119], v[82:83] op_sel_hi:[0,1]
	v_pk_mul_f32 v[84:85], v[118:119], v[84:85] op_sel_hi:[0,1]
	v_div_fixup_f32 v118, v117, v121, 1.0
	v_div_fmas_f32 v117, v122, v131, v135
	s_mov_b64 vcc, s[8:9]
	v_pk_fma_f32 v[112:113], v[26:27], v[112:113], v[0:1]
	v_pk_fma_f32 v[108:109], v[28:29], v[108:109], v[2:3]
	v_pk_fma_f32 v[106:107], v[30:31], v[106:107], v[4:5]
	v_pk_fma_f32 v[104:105], v[32:33], v[104:105], v[6:7]
	v_pk_fma_f32 v[110:111], v[34:35], v[110:111], v[8:9]
	v_pk_fma_f32 v[120:121], v[36:37], v[80:81], v[10:11] op_sel:[0,1,0] op_sel_hi:[1,0,1]
	v_pk_fma_f32 v[82:83], v[38:39], v[82:83], v[12:13] op_sel:[0,1,0] op_sel_hi:[1,0,1]
	v_pk_fma_f32 v[84:85], v[40:41], v[84:85], v[14:15] op_sel:[0,1,0] op_sel_hi:[1,0,1]
	v_pk_mul_f32 v[102:103], v[118:119], v[102:103] op_sel_hi:[0,1]
	v_pk_mul_f32 v[98:99], v[118:119], v[98:99] op_sel_hi:[0,1]
	v_pk_mul_f32 v[96:97], v[118:119], v[96:97] op_sel_hi:[0,1]
	v_pk_mul_f32 v[94:95], v[118:119], v[94:95] op_sel_hi:[0,1]
	v_pk_mul_f32 v[100:101], v[118:119], v[100:101] op_sel_hi:[0,1]
	v_pk_mul_f32 v[122:123], v[118:119], v[66:67] op_sel_hi:[0,1]
	v_pk_mul_f32 v[124:125], v[118:119], v[68:69] op_sel_hi:[0,1]
	v_pk_mul_f32 v[72:73], v[118:119], v[72:73] op_sel_hi:[0,1]
	v_div_fixup_f32 v118, v117, v119, 1.0
	v_div_fmas_f32 v117, v127, v132, v136
	v_cvt_pk_bf16_f32 v66, v112, v113
	v_cvt_pk_bf16_f32 v67, v108, v109
	v_cvt_pk_bf16_f32 v68, v106, v107
	v_cvt_pk_bf16_f32 v69, v104, v105
	v_cvt_pk_bf16_f32 v80, v110, v111
	v_cvt_pk_bf16_f32 v81, v120, v121
	v_cvt_pk_bf16_f32 v82, v82, v83
	v_cvt_pk_bf16_f32 v83, v84, v85
	v_pk_fma_f32 v[84:85], v[26:27], v[102:103], v[0:1]
; __device__ __forceinline__ unsigned pk2(float lo, float hi) { f32x2 v = {lo, hi}; bf16x2_t b = __builtin_convertvector(v, bf16x2_t); return __builtin_bit_cast(unsigned, b); }
; __device__ __forceinline__ void norm_mod_bf16_phase(const Ctx& F, const bf16_t* xin, const float* gain, const float* shift, const float* scale) {
;     ...
;             for (int u = 0; u < 4; ++u) { const float rstd = 1.0f / sqrtf(s[u] * (1.0f / D) + 1e-6f);
; #pragma unroll
;                 for (int j = 0; j < 2; ++j) { float f[8]; unpack8(raw[u][j], f); float o[8];
; #pragma unroll
;                     for (int e = 0; e < 8; ++e) o[e] = f[e] * rstd * ga[j][e] + sh[j][e];
;                     u32x4 w; w.x = pk2(o[0], o[1]); w.y = pk2(o[2], o[3]); w.z = pk2(o[4], o[5]); w.w = pk2(o[6], o[7]);
;                     *(u32x4*)(hb + (size_t)(row0 + r + u) * D + 8 * ln + 512 * j) = w; } }
;         }
;     }
	v_pk_fma_f32 v[98:99], v[28:29], v[98:99], v[2:3]
	v_pk_fma_f32 v[96:97], v[30:31], v[96:97], v[4:5]
	v_pk_fma_f32 v[94:95], v[32:33], v[94:95], v[6:7]
	v_pk_fma_f32 v[72:73], v[40:41], v[72:73], v[14:15] op_sel:[0,1,0] op_sel_hi:[1,0,1]
	v_pk_mul_f32 v[92:93], v[118:119], v[92:93] op_sel_hi:[0,1]
	v_pk_mul_f32 v[88:89], v[118:119], v[88:89] op_sel_hi:[0,1]
	v_pk_mul_f32 v[86:87], v[118:119], v[86:87] op_sel_hi:[0,1]
	v_pk_mul_f32 v[78:79], v[118:119], v[78:79] op_sel_hi:[0,1]
	v_pk_mul_f32 v[60:61], v[118:119], v[60:61] op_sel_hi:[0,1]
	v_div_fixup_f32 v110, v117, v126, 1.0
	v_pk_fma_f32 v[100:101], v[34:35], v[100:101], v[8:9]
	v_pk_fma_f32 v[102:103], v[36:37], v[122:123], v[10:11] op_sel:[0,1,0] op_sel_hi:[1,0,1]
	v_pk_fma_f32 v[104:105], v[38:39], v[124:125], v[12:13] op_sel:[0,1,0] op_sel_hi:[1,0,1]
	v_pk_mul_f32 v[90:91], v[118:119], v[90:91] op_sel_hi:[0,1]
	v_pk_mul_f32 v[106:107], v[118:119], v[56:57] op_sel_hi:[0,1]
	v_pk_mul_f32 v[108:109], v[118:119], v[58:59] op_sel_hi:[0,1]
	global_store_dwordx4 v[48:49], v[66:69], off
	global_store_dwordx4 v[48:49], v[80:83], off offset:1024
	v_cvt_pk_bf16_f32 v56, v84, v85
	v_cvt_pk_bf16_f32 v57, v98, v99
	v_cvt_pk_bf16_f32 v58, v96, v97
	v_cvt_pk_bf16_f32 v59, v94, v95
	v_cvt_pk_bf16_f32 v69, v72, v73
	v_pk_fma_f32 v[48:49], v[26:27], v[92:93], v[0:1]
	v_pk_fma_f32 v[72:73], v[28:29], v[88:89], v[2:3]
	v_pk_fma_f32 v[80:81], v[30:31], v[86:87], v[4:5]
	v_pk_fma_f32 v[78:79], v[32:33], v[78:79], v[6:7]
	v_pk_fma_f32 v[60:61], v[40:41], v[60:61], v[14:15] op_sel:[0,1,0] op_sel_hi:[1,0,1]
	v_pk_mul_f32 v[76:77], v[110:111], v[76:77] op_sel_hi:[0,1]
	v_pk_mul_f32 v[70:71], v[110:111], v[70:71] op_sel_hi:[0,1]
	v_pk_mul_f32 v[64:65], v[110:111], v[64:65] op_sel_hi:[0,1]
	v_pk_mul_f32 v[62:63], v[110:111], v[62:63] op_sel_hi:[0,1]
	v_cvt_pk_bf16_f32 v66, v100, v101
	v_cvt_pk_bf16_f32 v67, v102, v103
	v_cvt_pk_bf16_f32 v68, v104, v105
	v_pk_fma_f32 v[82:83], v[34:35], v[90:91], v[8:9]
	v_pk_fma_f32 v[84:85], v[36:37], v[106:107], v[10:11] op_sel:[0,1,0] op_sel_hi:[1,0,1]
	v_pk_fma_f32 v[86:87], v[38:39], v[108:109], v[12:13] op_sel:[0,1,0] op_sel_hi:[1,0,1]
	v_pk_mul_f32 v[74:75], v[110:111], v[74:75] op_sel_hi:[0,1]
	v_pk_mul_f32 v[88:89], v[110:111], v[50:51] op_sel_hi:[0,1]
	v_pk_mul_f32 v[90:91], v[110:111], v[52:53] op_sel_hi:[0,1]
	v_pk_mul_f32 v[54:55], v[110:111], v[54:55] op_sel_hi:[0,1]
	global_store_dwordx4 v[46:47], v[56:59], off
	global_store_dwordx4 v[46:47], v[66:69], off offset:1024
	v_cvt_pk_bf16_f32 v46, v48, v49
	v_cvt_pk_bf16_f32 v47, v72, v73
	v_cvt_pk_bf16_f32 v48, v80, v81
	v_cvt_pk_bf16_f32 v49, v78, v79
	v_cvt_pk_bf16_f32 v53, v60, v61
	v_pk_fma_f32 v[56:57], v[26:27], v[76:77], v[0:1]
	v_pk_fma_f32 v[58:59], v[28:29], v[70:71], v[2:3]
	v_pk_fma_f32 v[60:61], v[30:31], v[64:65], v[4:5]
	v_pk_fma_f32 v[62:63], v[32:33], v[62:63], v[6:7]
	v_cvt_pk_bf16_f32 v50, v82, v83
	v_cvt_pk_bf16_f32 v51, v84, v85
	v_cvt_pk_bf16_f32 v52, v86, v87
	v_pk_fma_f32 v[64:65], v[34:35], v[74:75], v[8:9]
	v_pk_fma_f32 v[66:67], v[36:37], v[88:89], v[10:11] op_sel:[0,1,0] op_sel_hi:[1,0,1]
	v_pk_fma_f32 v[68:69], v[38:39], v[90:91], v[12:13] op_sel:[0,1,0] op_sel_hi:[1,0,1]
	v_pk_fma_f32 v[54:55], v[40:41], v[54:55], v[14:15] op_sel:[0,1,0] op_sel_hi:[1,0,1]
	global_store_dwordx4 v[44:45], v[46:49], off
	global_store_dwordx4 v[44:45], v[50:53], off offset:1024
	v_cvt_pk_bf16_f32 v44, v56, v57
	v_cvt_pk_bf16_f32 v45, v58, v59
	v_cvt_pk_bf16_f32 v46, v60, v61
	v_cvt_pk_bf16_f32 v47, v62, v63
	v_cvt_pk_bf16_f32 v48, v64, v65
	v_cvt_pk_bf16_f32 v49, v66, v67
	v_cvt_pk_bf16_f32 v50, v68, v69
	v_cvt_pk_bf16_f32 v51, v54, v55
	global_store_dwordx4 v[42:43], v[44:47], off
	global_store_dwordx4 v[42:43], v[48:51], off offset:1024
	s_waitcnt vmcnt(8)
	s_cbranch_scc0 .LBB0_1204
	s_add_i32 s0, s0, s1
	s_add_i32 s18, s18, s3
	s_add_i32 s20, s20, s3
	s_add_i32 s22, s22, s3
	s_add_i32 s24, s24, s3
	s_cmpk_gt_i32 s0, 0x7ff
	s_cbranch_scc0 .LBB0_1203
